# gdn_prep forward substitution: dense block update on f32 MFMA 16x16x4 (L fragment via ds_read_b128, X via ds_read_b32) instead of per-thread LDS loop
# speedup vs baseline: 1.2024x; 1.0149x over previous
; DI void phase_gdn_prep(const Params& p, int l, char* smem) {
;     ...
;             if (rb > 0) {
;                 const int j = tid & 127, rh = tid >> 7;
;                 float* X = (j < 64) ? sv : sk; const int col = j & 63;
;                 const int r0 = rb * 16 + rh * 8;
;                 float a[8];
; #pragma unroll
;                 for (int i = 0; i < 8; ++i) a[i] = 0.f;
;                 for (int s4 = 0; s4 < rb * 16; s4 += 4) {
;                     const float x0 = X[(s4 + 0) * 65 + col], x1 = X[(s4 + 1) * 65 + col], x2 = X[(s4 + 2) * 65 + col], x3 = X[(s4 + 3) * 65 + col];
; #pragma unroll
;                     for (int i = 0; i < 8; ++i) {
;                         const f32x4 lv = *(const f32x4*)(sL + (r0 + i) * 64 + s4);
;                         a[i] += lv[0] * x0 + lv[1] * x1 + lv[2] * x2 + lv[3] * x3;
;                     }
;                 }
; #pragma unroll
;                 for (int i = 0; i < 8; ++i) X[(r0 + i) * 65 + col] -= a[i];
;                 __syncthreads();
;             }
.LBB0_335:
	s_cmp_eq_u32 s4, 0
	s_cbranch_scc1 .LBB0_339
	v_and_b32_e32 v204, 15, v62
	v_lshrrev_b32_e32 v205, 4, v62
	v_lshlrev_b32_e32 v186, 8, v204
	v_lshl_add_u32 v186, v205, 4, v186
	s_lshl_b32 s5, s4, 12
	s_add_i32 s5, s5, 0xc300
	v_add_u32_e32 v186, s5, v186
	v_mul_u32_u24_e32 v187, 0x410, v205
	v_lshl_add_u32 v187, v204, 2, v187
	v_and_b32_e32 v206, 64, v40
	v_lshl_add_u32 v187, v206, 1, v187
	v_mov_b32_e32 v206, 0x8200
	v_mov_b32_e32 v207, 0x4100
	s_mul_i32 s5, s4, 0x1040
	v_cndmask_b32_e64 v206, v207, v206, s[48:49]
	v_add_u32_e32 v187, v187, v206
	v_add_u32_e32 v188, s5, v187
	ds_read_b128 v[192:195], v186 offset:0
	ds_read_b32 v196, v187 offset:0
	ds_read_b32 v197, v187 offset:64
	ds_read_b32 v198, v187 offset:260
	ds_read_b32 v199, v187 offset:324
	ds_read_b32 v200, v187 offset:520
	ds_read_b32 v201, v187 offset:584
	ds_read_b32 v202, v187 offset:780
	ds_read_b32 v203, v187 offset:844
	s_cmp_lt_u32 s4, 2
	s_cbranch_scc1 .Lgd_1
	ds_read_b128 v[36:39], v186 offset:64
	ds_read_b32 v58, v187 offset:4160
	ds_read_b32 v59, v187 offset:4224
	ds_read_b32 v60, v187 offset:4420
	ds_read_b32 v61, v187 offset:4484
	ds_read_b32 v204, v187 offset:4680
	ds_read_b32 v205, v187 offset:4744
	ds_read_b32 v206, v187 offset:4940
	ds_read_b32 v207, v187 offset:5004
	s_waitcnt lgkmcnt(9)
	v_mfma_f32_16x16x4_f32 v[230:233], v192, v196, 0
	v_mfma_f32_16x16x4_f32 v[234:237], v192, v197, 0
	v_mfma_f32_16x16x4_f32 v[230:233], v193, v198, v[230:233]
	v_mfma_f32_16x16x4_f32 v[234:237], v193, v199, v[234:237]
	v_mfma_f32_16x16x4_f32 v[230:233], v194, v200, v[230:233]
	v_mfma_f32_16x16x4_f32 v[234:237], v194, v201, v[234:237]
	v_mfma_f32_16x16x4_f32 v[230:233], v195, v202, v[230:233]
	v_mfma_f32_16x16x4_f32 v[234:237], v195, v203, v[234:237]
	s_cmp_lt_u32 s4, 3
	s_cbranch_scc1 .Lgd_2
	ds_read_b128 v[192:195], v186 offset:128
	ds_read_b32 v196, v187 offset:8320
	ds_read_b32 v197, v187 offset:8384
	ds_read_b32 v198, v187 offset:8580
	ds_read_b32 v199, v187 offset:8644
	ds_read_b32 v200, v187 offset:8840
	ds_read_b32 v201, v187 offset:8904
	ds_read_b32 v202, v187 offset:9100
	ds_read_b32 v203, v187 offset:9164
	s_waitcnt lgkmcnt(9)
	v_mfma_f32_16x16x4_f32 v[230:233], v36, v58, v[230:233]
	v_mfma_f32_16x16x4_f32 v[234:237], v36, v59, v[234:237]
	v_mfma_f32_16x16x4_f32 v[230:233], v37, v60, v[230:233]
	v_mfma_f32_16x16x4_f32 v[234:237], v37, v61, v[234:237]
	v_mfma_f32_16x16x4_f32 v[230:233], v38, v204, v[230:233]
	v_mfma_f32_16x16x4_f32 v[234:237], v38, v205, v[234:237]
	v_mfma_f32_16x16x4_f32 v[230:233], v39, v206, v[230:233]
	v_mfma_f32_16x16x4_f32 v[234:237], v39, v207, v[234:237]
	s_waitcnt lgkmcnt(0)
	v_mfma_f32_16x16x4_f32 v[230:233], v192, v196, v[230:233]
	v_mfma_f32_16x16x4_f32 v[234:237], v192, v197, v[234:237]
	v_mfma_f32_16x16x4_f32 v[230:233], v193, v198, v[230:233]
	v_mfma_f32_16x16x4_f32 v[234:237], v193, v199, v[234:237]
	v_mfma_f32_16x16x4_f32 v[230:233], v194, v200, v[230:233]
	v_mfma_f32_16x16x4_f32 v[234:237], v194, v201, v[234:237]
	v_mfma_f32_16x16x4_f32 v[230:233], v195, v202, v[230:233]
	v_mfma_f32_16x16x4_f32 v[234:237], v195, v203, v[234:237]
	s_branch .Lgd_upd
.Lgd_1:
	s_waitcnt lgkmcnt(0)
	v_mfma_f32_16x16x4_f32 v[230:233], v192, v196, 0
	v_mfma_f32_16x16x4_f32 v[234:237], v192, v197, 0
	v_mfma_f32_16x16x4_f32 v[230:233], v193, v198, v[230:233]
	v_mfma_f32_16x16x4_f32 v[234:237], v193, v199, v[234:237]
	v_mfma_f32_16x16x4_f32 v[230:233], v194, v200, v[230:233]
	v_mfma_f32_16x16x4_f32 v[234:237], v194, v201, v[234:237]
	v_mfma_f32_16x16x4_f32 v[230:233], v195, v202, v[230:233]
	v_mfma_f32_16x16x4_f32 v[234:237], v195, v203, v[234:237]
	s_branch .Lgd_upd
.Lgd_2:
	s_waitcnt lgkmcnt(0)
	v_mfma_f32_16x16x4_f32 v[230:233], v36, v58, v[230:233]
	v_mfma_f32_16x16x4_f32 v[234:237], v36, v59, v[234:237]
	v_mfma_f32_16x16x4_f32 v[230:233], v37, v60, v[230:233]
	v_mfma_f32_16x16x4_f32 v[234:237], v37, v61, v[234:237]
	v_mfma_f32_16x16x4_f32 v[230:233], v38, v204, v[230:233]
	v_mfma_f32_16x16x4_f32 v[234:237], v38, v205, v[234:237]
	v_mfma_f32_16x16x4_f32 v[230:233], v39, v206, v[230:233]
	v_mfma_f32_16x16x4_f32 v[234:237], v39, v207, v[234:237]
.Lgd_upd:
	ds_read_b32 v196, v188 offset:0
	ds_read_b32 v197, v188 offset:260
	ds_read_b32 v198, v188 offset:520
	ds_read_b32 v199, v188 offset:780
	ds_read_b32 v200, v188 offset:64
	ds_read_b32 v201, v188 offset:324
	ds_read_b32 v202, v188 offset:584
	ds_read_b32 v203, v188 offset:844
	s_nop 4
	s_waitcnt lgkmcnt(0)
	v_sub_f32_e32 v196, v196, v230
	v_sub_f32_e32 v197, v197, v231
	v_sub_f32_e32 v198, v198, v232
	v_sub_f32_e32 v199, v199, v233
	v_sub_f32_e32 v200, v200, v234
	v_sub_f32_e32 v201, v201, v235
	v_sub_f32_e32 v202, v202, v236
	v_sub_f32_e32 v203, v203, v237
	ds_write_b32 v188, v196 offset:0
	ds_write_b32 v188, v197 offset:260
	ds_write_b32 v188, v198 offset:520
	ds_write_b32 v188, v199 offset:780
	ds_write_b32 v188, v200 offset:64
	ds_write_b32 v188, v201 offset:324
	ds_write_b32 v188, v202 offset:584
	ds_write_b32 v188, v203 offset:844
	s_waitcnt lgkmcnt(0)
	s_barrier
